# GEMM unit headers: next-tile index of the static order in closed form (shifts/masks) instead of the XCD permutation + integer division sequence
# speedup vs baseline: 1.0072x; 1.0014x over previous
;     __host__ __device__ bool next(int i, Unit& u) const {
;         const long L = (long)i * G + c; if (L >= nwg) return false;
;         int wgid = (int)L; { const int q = nwg / NXCD, r = nwg % NXCD, xcd = wgid % NXCD, off = wgid / NXCD; wgid = (xcd < r ? xcd * (q + 1) : r * (q + 1) + (xcd - r) * q) + off; }
;         const int nig = WGM * nN, gid = wgid / nig, fm = gid * WGM, gsz = (nM - fm) < WGM ? (nM - fm) : WGM;
;         u.pm = fm + ((wgid % nig) % gsz); u.pn = (wgid % nig) / gsz; return true;
;     }
.LBB0_29:
	s_add_i32 s34, s34, 1
	s_mul_i32 s37, s34, s53
	s_mul_hi_u32 s42, s34, s52
	s_add_i32 s42, s42, s37
	s_mul_i32 s37, s34, s52
	s_add_u32 s58, s37, s2
	s_addc_u32 s59, s42, s61
	v_cmp_gt_i64_e32 vcc, s[58:59], v[132:133]
	v_cmp_lt_i64_e64 s[42:43], s[58:59], v[130:131]
	s_cbranch_vccnz .LBB0_35
	s_and_b32 s44, s58, 7
	s_lshl_b32 s44, s44, 3
	s_bfe_u32 s36, s58, 0x30003
	s_add_i32 s44, s44, s36
	s_lshr_b32 s36, s58, 6

;     __host__ __device__ bool next(int i, Unit& u) const {
;         const long L = (long)i * G + c; if (L >= nwg) return false;
;         int wgid = (int)L; { const int q = nwg / NXCD, r = nwg % NXCD, xcd = wgid % NXCD, off = wgid / NXCD; wgid = (xcd < r ? xcd * (q + 1) : r * (q + 1) + (xcd - r) * q) + off; }
;         const int nig = WGM * nN, gid = wgid / nig, fm = gid * WGM, gsz = (nM - fm) < WGM ? (nM - fm) : WGM;
;         u.pm = fm + ((wgid % nig) % gsz); u.pn = (wgid % nig) / gsz; return true;
;     }
.LBB0_69:
	s_add_i32 s30, s30, 1
	s_mul_i32 s18, s30, s53
	s_mul_hi_u32 s19, s30, s52
	s_add_i32 s19, s19, s18
	s_mul_i32 s18, s30, s52
	s_add_u32 s18, s18, s2
	s_addc_u32 s19, s19, s61
	v_cmp_gt_i64_e32 vcc, s[18:19], v[136:137]
	v_cmp_lt_i64_e64 s[40:41], s[18:19], v[134:135]
	s_cbranch_vccnz .LBB0_75
	s_and_b32 s96, s18, 7
	s_lshl_b32 s96, s96, 3
	s_bfe_u32 s44, s18, 0x30003
	s_add_i32 s96, s96, s44
	s_lshr_b32 s44, s18, 6

; #define PG8_STAGE(bufoff, gbase, voff) do { _Pragma("unroll") for (int _i = 0; _i < 2; ++_i) \
;         __builtin_amdgcn_global_load_lds((const unsigned*)((const char*)(gbase) + (voff)[_i]), (PG8_LAS unsigned*)(lds + (bufoff) + ldsw + _i * 8192), 16, 0, 0); } while (0)
; #define PG8_LDA(dst, b, h) do { _Pragma("unroll") for (int m = 0; m < 4; ++m) _Pragma("unroll") for (int k = 0; k < 2; ++k) dst[m][k] = *(const PG8_LAS bf16x8*)(lds + PG8_SA(b, h) + aoff + m * 2048 + k * 1024); } while (0)
; #define PG8_LDB(dst, b, h) do { _Pragma("unroll") for (int n = 0; n < 2; ++n) _Pragma("unroll") for (int k = 0; k < 2; ++k) dst[n][k] = *(const PG8_LAS bf16x8*)(lds + PG8_SB(b, h) + boff + n * 2048 + k * 1024); } while (0)
; #define PG8_MMA(ai, bj, At, Bt) do { __builtin_amdgcn_s_setprio(1); _Pragma("unroll") for (int m = 0; m < 4; ++m) _Pragma("unroll") for (int n = 0; n < 2; ++n) _Pragma("unroll") for (int k = 0; k < 2; ++k) \
;         acc[ai][bj][m][n] = __builtin_amdgcn_mfma_f32_16x16x32_bf16(Bt[n][k], At[m][k], acc[ai][bj][m][n], 0, 0, 0); __builtin_amdgcn_s_setprio(0); } while (0)
; #define PG8_WAIT_V(n) asm volatile("s_waitcnt vmcnt(" #n ")" ::: "memory")
; #define PG8_WAIT_L(n) asm volatile("s_waitcnt lgkmcnt(" #n ")" ::: "memory")
; #define PG8_BAR __builtin_amdgcn_s_barrier()
; #define PG8_SCHED __builtin_amdgcn_sched_barrier(0)
; template <class Epi, class Sched, bool ALIGN_EPI = false, bool SP2 = false>
; __device__ __forceinline__ void gemm_phase(PG8_LAS unsigned char* lds, const Gemm g, const Sched& S, const Epi& E) {
;     ...
;             PG8_LDB(B0, 0, 0); PG8_LDB(B1, 0, 1); PG8_SCHED; PG8_LDA(At, 0, 0); PG8_STAGE(PG8_SA(1, 1), a1 + hstep, voffA);
;             PG8_WAIT_V(8); PG8_WAIT_L(0); PG8_BAR; PG8_MMA(0, 0, At, B0); PG8_MMA(0, 1, At, B1); PG8_BAR; PG8_SCHED;
;             PG8_LDA(At, 0, 1); PG8_STAGE(PG8_SB(0, 0), b2, voffB); PG8_STAGE(PG8_SB(0, 1), b2 + hstep, voffB); PG8_STAGE(PG8_SA(0, 0), a2, voffA);
;             PG8_WAIT_V(8); PG8_WAIT_L(0); PG8_BAR; PG8_MMA(1, 0, At, B0); PG8_MMA(1, 1, At, B1); PG8_BAR; PG8_SCHED;
.Lpw3_j:
	s_nop 0
	s_nop 0
	s_waitcnt lgkmcnt(0)
	s_setprio 1
	s_barrier
	v_mfma_f32_16x16x32_bf16 v[126:129], v[162:165], v[212:215], 0
	v_mfma_f32_16x16x32_bf16 v[122:125], v[170:173], v[212:215], 0
	v_mfma_f32_16x16x32_bf16 v[110:113], v[162:165], v[220:223], 0
	v_mfma_f32_16x16x32_bf16 v[106:109], v[170:173], v[220:223], 0
	v_mfma_f32_16x16x32_bf16 v[94:97], v[162:165], v[228:231], 0
	v_mfma_f32_16x16x32_bf16 v[90:93], v[170:173], v[228:231], 0
	v_mfma_f32_16x16x32_bf16 v[78:81], v[162:165], v[236:239], 0
	v_mfma_f32_16x16x32_bf16 v[74:77], v[170:173], v[236:239], 0
	s_setprio 0
	s_setprio 1
	v_mfma_f32_16x16x32_bf16 v[126:129], v[166:169], v[216:219], v[126:129]
	v_mfma_f32_16x16x32_bf16 v[122:125], v[174:177], v[216:219], v[122:125]
	v_mfma_f32_16x16x32_bf16 v[110:113], v[166:169], v[224:227], v[110:113]
	v_mfma_f32_16x16x32_bf16 v[106:109], v[174:177], v[224:227], v[106:109]
	v_mfma_f32_16x16x32_bf16 v[94:97], v[166:169], v[232:235], v[94:97]
	v_mfma_f32_16x16x32_bf16 v[90:93], v[174:177], v[232:235], v[90:93]
	v_mfma_f32_16x16x32_bf16 v[78:81], v[166:169], v[240:243], v[78:81]
	v_mfma_f32_16x16x32_bf16 v[74:77], v[174:177], v[240:243], v[74:77]
	s_setprio 0
	s_setprio 1
	v_mfma_f32_16x16x32_bf16 v[118:121], v[178:181], v[212:215], 0
	v_mfma_f32_16x16x32_bf16 v[114:117], v[204:207], v[212:215], 0
	v_mfma_f32_16x16x32_bf16 v[102:105], v[178:181], v[220:223], 0
	v_mfma_f32_16x16x32_bf16 v[98:101], v[204:207], v[220:223], 0
	v_mfma_f32_16x16x32_bf16 v[86:89], v[178:181], v[228:231], 0
	v_mfma_f32_16x16x32_bf16 v[82:85], v[204:207], v[228:231], 0
	v_mfma_f32_16x16x32_bf16 v[70:73], v[178:181], v[236:239], 0
	v_mfma_f32_16x16x32_bf16 v[66:69], v[204:207], v[236:239], 0
	s_setprio 0
	s_setprio 1
	v_mfma_f32_16x16x32_bf16 v[118:121], v[182:185], v[216:219], v[118:121]
	v_mfma_f32_16x16x32_bf16 v[114:117], v[208:211], v[216:219], v[114:117]
	v_mfma_f32_16x16x32_bf16 v[102:105], v[182:185], v[224:227], v[102:105]
	v_mfma_f32_16x16x32_bf16 v[98:101], v[208:211], v[224:227], v[98:101]
	v_mfma_f32_16x16x32_bf16 v[86:89], v[182:185], v[232:235], v[86:89]
	v_mfma_f32_16x16x32_bf16 v[82:85], v[208:211], v[232:235], v[82:85]
	v_mfma_f32_16x16x32_bf16 v[70:73], v[182:185], v[240:243], v[70:73]
	v_mfma_f32_16x16x32_bf16 v[66:69], v[208:211], v[240:243], v[66:69]
	s_setprio 0
	s_barrier
	s_add_i32 s47, s47, s54
	v_lshl_add_u64 v[158:159], s[18:19], 0, v[148:149]
	s_mov_b32 m0, s47
	ds_read_b128 v[212:215], v161 offset:16384
	ds_read_b128 v[216:219], v161 offset:17408
	ds_read_b128 v[220:223], v161 offset:18432
	ds_read_b128 v[224:227], v161 offset:19456
	ds_read_b128 v[228:231], v161 offset:20480
	ds_read_b128 v[232:235], v161 offset:21504
	ds_read_b128 v[236:239], v161 offset:22528
	ds_read_b128 v[240:243], v161 offset:23552
	global_load_lds_dwordx4 v[158:159], off
	s_add_i32 m0, s47, 0x2000
	s_add_u32 s76, s18, 0x80000
	v_lshl_add_u64 v[186:187], s[18:19], 0, v[144:145]
	s_addc_u32 s77, s19, 0
	s_add_i32 s47, s80, s54
	global_load_lds_dwordx4 v[186:187], off
	v_lshl_add_u64 v[244:245], s[76:77], 0, v[148:149]
	s_mov_b32 m0, s47
	v_lshl_add_u64 v[246:247], s[58:59], 0, v[146:147]
	global_load_lds_dwordx4 v[244:245], off
	v_lshl_add_u64 v[244:245], s[76:77], 0, v[144:145]
	s_add_i32 m0, s47, 0x2000
	s_nop 0
	global_load_lds_dwordx4 v[244:245], off
	v_lshl_add_u64 v[244:245], s[58:59], 0, v[150:151]
	s_mov_b32 m0, s62
	s_nop 0
	global_load_lds_dwordx4 v[244:245], off
	s_mov_b32 m0, s63
	s_nop 0
	global_load_lds_dwordx4 v[246:247], off
	s_cmp_eq_u32 s32, 0
	s_cbranch_scc1 .Lpw4_f
	s_waitcnt vmcnt(24)
	s_branch .Lpw4_j

;     __host__ __device__ bool next(int i, Unit& u) const {
;         const long L = (long)i * G + c; if (L >= nwg) return false;
;         int wgid = (int)L; { const int q = nwg / NXCD, r = nwg % NXCD, xcd = wgid % NXCD, off = wgid / NXCD; wgid = (xcd < r ? xcd * (q + 1) : r * (q + 1) + (xcd - r) * q) + off; }
;         const int nig = WGM * nN, gid = wgid / nig, fm = gid * WGM, gsz = (nM - fm) < WGM ? (nM - fm) : WGM;
;         u.pm = fm + ((wgid % nig) % gsz); u.pn = (wgid % nig) / gsz; return true;
;     }
.LBB0_91:
	s_add_i32 s86, s86, 1
	s_mul_i32 s18, s86, s53
	s_mul_hi_u32 s19, s86, s52
	s_add_i32 s19, s19, s18
	s_mul_i32 s18, s86, s52
	s_add_u32 s18, s18, s2
	s_addc_u32 s19, s19, s61
	v_cmp_gt_i64_e32 vcc, s[18:19], v[132:133]
	v_cmp_lt_i64_e64 s[44:45], s[18:19], v[130:131]
	s_cbranch_vccnz .LBB0_97
	s_and_b32 s96, s18, 7
	s_lshl_b32 s96, s96, 3
	s_bfe_u32 s94, s18, 0x30003
	s_add_i32 s96, s96, s94
	s_lshr_b32 s94, s18, 6

;     __host__ __device__ bool next(int i, Unit& u) const {
;         const long L = (long)i * G + c; if (L >= nwg) return false;
;         int wgid = (int)L; { const int q = nwg / NXCD, r = nwg % NXCD, xcd = wgid % NXCD, off = wgid / NXCD; wgid = (xcd < r ? xcd * (q + 1) : r * (q + 1) + (xcd - r) * q) + off; }
;         const int nig = WGM * nN, gid = wgid / nig, fm = gid * WGM, gsz = (nM - fm) < WGM ? (nM - fm) : WGM;
;         u.pm = fm + ((wgid % nig) % gsz); u.pn = (wgid % nig) / gsz; return true;
;     }
.LBB0_129:
	s_add_i32 s60, s60, 1
	s_mul_i32 s11, s60, s53
	s_mul_hi_u32 s37, s60, s52
	s_add_i32 s37, s37, s11
	s_mul_i32 s11, s60, s52
	s_add_u32 s40, s11, s2
	s_addc_u32 s41, s37, s61
	v_cmp_gt_i64_e32 vcc, s[40:41], v[132:133]
	v_cmp_lt_i64_e64 s[42:43], s[40:41], v[130:131]
	s_cbranch_vccnz .LBB0_135
	s_and_b32 s36, s40, 7
	s_lshl_b32 s36, s36, 3
	s_bfe_u32 s10, s40, 0x30003
	s_add_i32 s36, s36, s10
	s_lshr_b32 s10, s40, 6

;     __host__ __device__ bool next(int i, Unit& u) const {
;         const long L = (long)i * G + c; if (L >= nwg) return false;
;         int wgid = (int)L; { const int q = nwg / NXCD, r = nwg % NXCD, xcd = wgid % NXCD, off = wgid / NXCD; wgid = (xcd < r ? xcd * (q + 1) : r * (q + 1) + (xcd - r) * q) + off; }
;         const int nig = WGM * nN, gid = wgid / nig, fm = gid * WGM, gsz = (nM - fm) < WGM ? (nM - fm) : WGM;
;         u.pm = fm + ((wgid % nig) % gsz); u.pn = (wgid % nig) / gsz; return true;
;     }
.LBB0_149:
	s_add_i32 s67, s67, 1
	s_mul_i32 s0, s67, s53
	s_mul_hi_u32 s1, s67, s52
	s_add_i32 s1, s1, s0
	s_mul_i32 s0, s67, s52
	s_add_u32 s6, s0, s2
	s_addc_u32 s7, s1, s61
	v_cmp_gt_i64_e32 vcc, s[6:7], v[132:133]
	v_cmp_lt_i64_e64 s[0:1], s[6:7], v[130:131]
	s_cbranch_vccnz .LBB0_155
	s_and_b32 s95, s6, 7
	s_lshl_b32 s95, s95, 3
	s_bfe_u32 s94, s6, 0x30003
	s_add_i32 s95, s95, s94
	s_lshr_b32 s94, s6, 6

;     __host__ __device__ bool next(int i, Unit& u) const {
;         const long L = (long)i * G + c; if (L >= nwg) return false;
;         int wgid = (int)L; { const int q = nwg / NXCD, r = nwg % NXCD, xcd = wgid % NXCD, off = wgid / NXCD; wgid = (xcd < r ? xcd * (q + 1) : r * (q + 1) + (xcd - r) * q) + off; }
;         const int nig = WGM * nN, gid = wgid / nig, fm = gid * WGM, gsz = (nM - fm) < WGM ? (nM - fm) : WGM;
;         u.pm = fm + ((wgid % nig) % gsz); u.pn = (wgid % nig) / gsz; return true;
;     }
.LBB0_278:
	s_add_i32 s54, s54, 1
	s_mul_i32 s7, s54, s53
	s_mul_hi_u32 s9, s54, s52
	s_add_i32 s9, s9, s7
	s_mul_i32 s7, s54, s52
	s_add_u32 s10, s7, s2
	s_addc_u32 s11, s9, s61
	v_cmp_gt_i64_e32 vcc, s[10:11], v[140:141]
	v_cmp_lt_i64_e64 s[40:41], s[10:11], v[138:139]
	s_cbranch_vccnz .LBB0_280
	s_and_b32 s8, s10, 7
	s_lshl_b32 s8, s8, 3
	s_bfe_u32 s6, s10, 0x30003
	s_add_i32 s8, s8, s6
	s_lshr_b32 s6, s10, 6

; #define PG8_STAGE(bufoff, gbase, voff) do { _Pragma("unroll") for (int _i = 0; _i < 2; ++_i) \
;         __builtin_amdgcn_global_load_lds((const unsigned*)((const char*)(gbase) + (voff)[_i]), (PG8_LAS unsigned*)(lds + (bufoff) + ldsw + _i * 8192), 16, 0, 0); } while (0)
; #define PG8_LDA(dst, b, h) do { _Pragma("unroll") for (int m = 0; m < 4; ++m) _Pragma("unroll") for (int k = 0; k < 2; ++k) dst[m][k] = *(const PG8_LAS bf16x8*)(lds + PG8_SA(b, h) + aoff + m * 2048 + k * 1024); } while (0)
; #define PG8_LDB(dst, b, h) do { _Pragma("unroll") for (int n = 0; n < 2; ++n) _Pragma("unroll") for (int k = 0; k < 2; ++k) dst[n][k] = *(const PG8_LAS bf16x8*)(lds + PG8_SB(b, h) + boff + n * 2048 + k * 1024); } while (0)
; #define PG8_MMA(ai, bj, At, Bt) do { __builtin_amdgcn_s_setprio(1); _Pragma("unroll") for (int m = 0; m < 4; ++m) _Pragma("unroll") for (int n = 0; n < 2; ++n) _Pragma("unroll") for (int k = 0; k < 2; ++k) \
;         acc[ai][bj][m][n] = __builtin_amdgcn_mfma_f32_16x16x32_bf16(Bt[n][k], At[m][k], acc[ai][bj][m][n], 0, 0, 0); __builtin_amdgcn_s_setprio(0); } while (0)
; #define PG8_WAIT_V(n) asm volatile("s_waitcnt vmcnt(" #n ")" ::: "memory")
; #define PG8_WAIT_L(n) asm volatile("s_waitcnt lgkmcnt(" #n ")" ::: "memory")
; #define PG8_BAR __builtin_amdgcn_s_barrier()
; #define PG8_SCHED __builtin_amdgcn_sched_barrier(0)
; template <class Epi, class Sched, bool ALIGN_EPI = false, bool SP2 = false>
; __device__ __forceinline__ void gemm_phase(PG8_LAS unsigned char* lds, const Gemm g, const Sched& S, const Epi& E) {
;     ...
;             PG8_LDB(B0, 0, 0); PG8_LDB(B1, 0, 1); PG8_SCHED; PG8_LDA(At, 0, 0); PG8_STAGE(PG8_SA(1, 1), a1 + hstep, voffA);
;             PG8_WAIT_V(8); PG8_WAIT_L(0); PG8_BAR; PG8_MMA(0, 0, At, B0); PG8_MMA(0, 1, At, B1); PG8_BAR; PG8_SCHED;
;             PG8_LDA(At, 0, 1); PG8_STAGE(PG8_SB(0, 0), b2, voffB); PG8_STAGE(PG8_SB(0, 1), b2 + hstep, voffB); PG8_STAGE(PG8_SA(0, 0), a2, voffA);
;             PG8_WAIT_V(8); PG8_WAIT_L(0); PG8_BAR; PG8_MMA(1, 0, At, B0); PG8_MMA(1, 1, At, B1); PG8_BAR; PG8_SCHED;
.Lpw11_j:
	s_nop 0
	s_waitcnt lgkmcnt(0)
	s_setprio 1
	s_barrier
	v_mfma_f32_16x16x32_bf16 v[126:129], v[156:159], v[208:211], 0
	v_mfma_f32_16x16x32_bf16 v[122:125], v[168:171], v[208:211], 0
	v_mfma_f32_16x16x32_bf16 v[110:113], v[156:159], v[216:219], 0
	v_mfma_f32_16x16x32_bf16 v[106:109], v[168:171], v[216:219], 0
	v_mfma_f32_16x16x32_bf16 v[94:97], v[156:159], v[224:227], 0
	v_mfma_f32_16x16x32_bf16 v[90:93], v[168:171], v[224:227], 0
	v_mfma_f32_16x16x32_bf16 v[78:81], v[156:159], v[232:235], 0
	v_mfma_f32_16x16x32_bf16 v[74:77], v[168:171], v[232:235], 0
	s_setprio 0
	s_setprio 1
	v_mfma_f32_16x16x32_bf16 v[126:129], v[164:167], v[212:215], v[126:129]
	v_mfma_f32_16x16x32_bf16 v[122:125], v[172:175], v[212:215], v[122:125]
	v_mfma_f32_16x16x32_bf16 v[110:113], v[164:167], v[220:223], v[110:113]
	v_mfma_f32_16x16x32_bf16 v[106:109], v[172:175], v[220:223], v[106:109]
	v_mfma_f32_16x16x32_bf16 v[94:97], v[164:167], v[228:231], v[94:97]
	v_mfma_f32_16x16x32_bf16 v[90:93], v[172:175], v[228:231], v[90:93]
	v_mfma_f32_16x16x32_bf16 v[78:81], v[164:167], v[236:239], v[78:81]
	v_mfma_f32_16x16x32_bf16 v[74:77], v[172:175], v[236:239], v[74:77]
	s_setprio 0
	s_setprio 1
	v_mfma_f32_16x16x32_bf16 v[118:121], v[176:179], v[208:211], 0
	v_mfma_f32_16x16x32_bf16 v[114:117], v[184:187], v[208:211], 0
	v_mfma_f32_16x16x32_bf16 v[102:105], v[176:179], v[216:219], 0
	v_mfma_f32_16x16x32_bf16 v[98:101], v[184:187], v[216:219], 0
	v_mfma_f32_16x16x32_bf16 v[86:89], v[176:179], v[224:227], 0
	v_mfma_f32_16x16x32_bf16 v[82:85], v[184:187], v[224:227], 0
	v_mfma_f32_16x16x32_bf16 v[70:73], v[176:179], v[232:235], 0
	v_mfma_f32_16x16x32_bf16 v[66:69], v[184:187], v[232:235], 0
	s_setprio 0
	s_setprio 1
	v_mfma_f32_16x16x32_bf16 v[118:121], v[180:183], v[212:215], v[118:121]
	v_mfma_f32_16x16x32_bf16 v[114:117], v[204:207], v[212:215], v[114:117]
	v_mfma_f32_16x16x32_bf16 v[102:105], v[180:183], v[220:223], v[102:105]
	v_mfma_f32_16x16x32_bf16 v[98:101], v[204:207], v[220:223], v[98:101]
	v_mfma_f32_16x16x32_bf16 v[86:89], v[180:183], v[228:231], v[86:89]
	v_mfma_f32_16x16x32_bf16 v[82:85], v[204:207], v[228:231], v[82:85]
	v_mfma_f32_16x16x32_bf16 v[70:73], v[180:183], v[236:239], v[70:73]
	v_mfma_f32_16x16x32_bf16 v[66:69], v[204:207], v[236:239], v[66:69]
	s_setprio 0
	s_barrier
	s_add_i32 s73, s73, s28
	v_lshl_add_u64 v[240:241], s[18:19], 0, v[146:147]
	s_mov_b32 m0, s73
	ds_read_b128 v[208:211], v162 offset:16384
	ds_read_b128 v[212:215], v162 offset:17408
	ds_read_b128 v[216:219], v162 offset:18432
	ds_read_b128 v[220:223], v162 offset:19456
	ds_read_b128 v[224:227], v162 offset:20480
	ds_read_b128 v[228:231], v162 offset:21504
	ds_read_b128 v[232:235], v162 offset:22528
	ds_read_b128 v[236:239], v162 offset:23552
	global_load_lds_dwordx4 v[240:241], off
	s_add_i32 m0, s73, 0x2000
	s_add_u32 s78, s18, 0x80000
	v_lshl_add_u64 v[242:243], s[18:19], 0, v[142:143]
	s_addc_u32 s79, s19, 0
	s_add_i32 s73, s76, s28
	global_load_lds_dwordx4 v[242:243], off
	v_lshl_add_u64 v[244:245], s[78:79], 0, v[146:147]
	s_mov_b32 m0, s73
	v_lshl_add_u64 v[246:247], s[42:43], 0, v[144:145]
	global_load_lds_dwordx4 v[244:245], off
	v_lshl_add_u64 v[244:245], s[78:79], 0, v[142:143]
	s_add_i32 m0, s73, 0x2000
	s_nop 0
	global_load_lds_dwordx4 v[244:245], off
	v_lshl_add_u64 v[244:245], s[42:43], 0, v[148:149]
	s_mov_b32 m0, s30
	s_nop 0
	global_load_lds_dwordx4 v[244:245], off
	s_mov_b32 m0, s34
	s_nop 0
	global_load_lds_dwordx4 v[246:247], off
	s_cmp_eq_u32 s32, 0
	s_cbranch_scc1 .Lpw12_f
	s_waitcnt vmcnt(16)
	s_branch .Lpw12_j
